# grid barrier release: all waiters poll the top-level arrival counter (>= (index+1)*nXCD) instead of the generation word
# baseline (speedup 1.0000x reference)
; __device__ __forceinline__ unsigned xb_ld(unsigned* p)              { return __hip_atomic_load(p, __ATOMIC_RELAXED, __HIP_MEMORY_SCOPE_AGENT); }
; __device__ __forceinline__ unsigned xb_add(unsigned* p, unsigned v) { return __hip_atomic_fetch_add(p, v, __ATOMIC_RELAXED, __HIP_MEMORY_SCOPE_AGENT); }
; #define XB_SPIN(cond, bar) do { unsigned _sp = 0; while (cond) { __builtin_amdgcn_s_sleep(1); \
;     if ((++_sp & 255u) == 0u) { if (xb_ld(&(bar)[XB_TMO])) break; if (_sp > XB_SPIN_CAP) { atomicAdd(&(bar)[XB_TMO], 1u); break; } } } } while (0)
; __device__ __forceinline__ void xcd_barrier(const XcdBarrier& b) {
;     ...
;         const unsigned old = xb_add(&bar[XB_XSUB(b.x)], 1u);
;         const unsigned gen = old / nloc;
;         if (old + 1u == (gen + 1u) * nloc) {
;             __builtin_amdgcn_fence(__ATOMIC_RELEASE, "agent");
;             asm volatile("s_waitcnt vmcnt(0)" ::: "memory");
;             const unsigned og = xb_add(&bar[XB_TOP], 1u);
;             const unsigned tg = og / nx;
;             if (og + 1u == (tg + 1u) * nx) xb_add(&bar[XB_TOPGEN], 1u);
;             else XB_SPIN(xb_ld(&bar[XB_TOPGEN]) == tg, bar);
;             __builtin_amdgcn_fence(__ATOMIC_ACQUIRE, "agent");
;             xb_add(&bar[XB_XGEN(b.x)], 1u);
;             asm volatile("s_waitcnt vmcnt(0)" ::: "memory");
;         } else {
;             XB_SPIN(xb_ld(&bar[XB_XGEN(b.x)]) == gen, bar);
;             __builtin_amdgcn_fence(__ATOMIC_ACQUIRE, "agent");
;             asm volatile("s_waitcnt vmcnt(0)" ::: "memory");
.LBB0_144:
	s_or_b64 exec, exec, s[8:9]
	v_cvt_f32_u32_e32 v5, v3
	s_waitcnt vmcnt(0)
	v_readfirstlane_b32 s3, v4
	v_sub_u32_e32 v4, 0, v3
	v_rcp_iflag_f32_e32 v5, v5
	v_add_u32_e32 v6, s3, v2
	v_mul_f32_e32 v5, 0x4f7ffffe, v5
	v_cvt_u32_f32_e32 v5, v5
	v_mul_lo_u32 v2, v4, v5
	v_mul_hi_u32 v2, v5, v2
	v_add_u32_e32 v2, v5, v2
	v_mul_hi_u32 v2, v6, v2
	v_mul_lo_u32 v4, v2, v3
	v_sub_u32_e32 v4, v6, v4
	v_add_u32_e32 v5, 1, v2
	v_cmp_ge_u32_e32 vcc, v4, v3
	s_nop 1
	v_cndmask_b32_e32 v2, v2, v5, vcc
	v_sub_u32_e32 v5, v4, v3
	v_cndmask_b32_e32 v4, v4, v5, vcc
	v_add_u32_e32 v5, 1, v2
	v_cmp_ge_u32_e32 vcc, v4, v3
	v_add_u32_e32 v4, 1, v6
	s_nop 0
	v_cndmask_b32_e32 v2, v2, v5, vcc
	v_mul_lo_u32 v5, v3, v2
	v_add_u32_e32 v3, v5, v3
	v_cmp_ne_u32_e32 vcc, v4, v3
	s_and_saveexec_b64 s[6:7], vcc
	s_xor_b64 s[6:7], exec, s[6:7]
	s_cbranch_execz .LBB0_158
	s_waitcnt lgkmcnt(0)
	v_add_u32_e32 v4, 1, v2
	v_mul_lo_u32 v4, v4, v1
	v_mov_b32_e32 v1, 0x3400
	global_load_dword v1, v1, s[30:31] sc1
	s_add_u32 s10, s30, 0x3400
	s_addc_u32 s11, s31, 0
	s_waitcnt vmcnt(0)
	v_cmp_lt_u32_e32 vcc, v1, v4
	s_and_saveexec_b64 s[8:9], vcc
	s_cbranch_execz .LBB0_157
	s_mov_b32 s3, 1
	s_mov_b64 s[12:13], 0
	v_mov_b32_e32 v1, 0
	s_branch .LBB0_148

; __device__ __forceinline__ unsigned xb_ld(unsigned* p)              { return __hip_atomic_load(p, __ATOMIC_RELAXED, __HIP_MEMORY_SCOPE_AGENT); }
; #define XB_SPIN(cond, bar) do { unsigned _sp = 0; while (cond) { __builtin_amdgcn_s_sleep(1); \
;     if ((++_sp & 255u) == 0u) { if (xb_ld(&(bar)[XB_TMO])) break; if (_sp > XB_SPIN_CAP) { atomicAdd(&(bar)[XB_TMO], 1u); break; } } } } while (0)
; __device__ __forceinline__ void xcd_barrier(const XcdBarrier& b) {
;     ...
;             XB_SPIN(xb_ld(&bar[XB_XGEN(b.x)]) == gen, bar);
.LBB0_150:
	global_load_dword v3, v1, s[10:11] sc1
	s_add_i32 s3, s3, 1
	s_mov_b64 s[38:39], -1
	s_waitcnt vmcnt(0)
	v_cmp_ge_u32_e32 vcc, v3, v4
	s_orn2_b64 s[16:17], vcc, exec
	s_branch .LBB0_147

; __device__ __forceinline__ unsigned xb_ld(unsigned* p)              { return __hip_atomic_load(p, __ATOMIC_RELAXED, __HIP_MEMORY_SCOPE_AGENT); }
; __device__ __forceinline__ unsigned xb_add(unsigned* p, unsigned v) { return __hip_atomic_fetch_add(p, v, __ATOMIC_RELAXED, __HIP_MEMORY_SCOPE_AGENT); }
; #define XB_SPIN(cond, bar) do { unsigned _sp = 0; while (cond) { __builtin_amdgcn_s_sleep(1); \
;     if ((++_sp & 255u) == 0u) { if (xb_ld(&(bar)[XB_TMO])) break; if (_sp > XB_SPIN_CAP) { atomicAdd(&(bar)[XB_TMO], 1u); break; } } } } while (0)
; __device__ __forceinline__ void xcd_barrier(const XcdBarrier& b) {
;     ...
;             const unsigned og = xb_add(&bar[XB_TOP], 1u);
;             const unsigned tg = og / nx;
;             if (og + 1u == (tg + 1u) * nx) xb_add(&bar[XB_TOPGEN], 1u);
;             else XB_SPIN(xb_ld(&bar[XB_TOPGEN]) == tg, bar);
;             __builtin_amdgcn_fence(__ATOMIC_ACQUIRE, "agent");
.LBB0_161:
	s_or_b64 exec, exec, s[10:11]
	v_cvt_f32_u32_e32 v4, v1
	s_waitcnt vmcnt(0)
	v_readfirstlane_b32 s3, v3
	s_add_u32 s10, s30, 0x3500
	s_addc_u32 s11, s31, 0
	v_rcp_iflag_f32_e32 v4, v4
	v_add_u32_e32 v2, s3, v2
	v_add_u32_e32 v5, 1, v2
	s_mov_b64 s[12:13], -1
	v_mul_f32_e32 v3, 0x4f7ffffe, v4
	v_cvt_u32_f32_e32 v3, v3
	v_sub_u32_e32 v4, 0, v1
	v_mul_lo_u32 v4, v4, v3
	v_mul_hi_u32 v4, v3, v4
	v_add_u32_e32 v3, v3, v4
	v_mul_hi_u32 v3, v2, v3
	v_mul_lo_u32 v4, v3, v1
	v_sub_u32_e32 v2, v2, v4
	v_add_u32_e32 v6, 1, v3
	v_cmp_ge_u32_e32 vcc, v2, v1
	v_sub_u32_e32 v4, v2, v1
	s_nop 0
	v_cndmask_b32_e32 v3, v3, v6, vcc
	v_cndmask_b32_e32 v2, v2, v4, vcc
	v_add_u32_e32 v4, 1, v3
	v_cmp_ge_u32_e32 vcc, v2, v1
	s_nop 1
	v_cndmask_b32_e32 v4, v3, v4, vcc
	v_mul_lo_u32 v2, v1, v4
	v_add_u32_e32 v1, v2, v1
	v_mov_b32_e32 v6, v1
	v_cmp_ne_u32_e32 vcc, v5, v1
	v_mov_b64_e32 v[2:3], s[10:11]
	s_and_saveexec_b64 s[8:9], vcc
	s_cbranch_execz .LBB0_173
	v_mov_b32_e32 v1, 0
	global_load_dword v2, v1, s[10:11] offset:-256 sc1
	s_mov_b64 s[16:17], 0
	s_waitcnt vmcnt(0)
	v_cmp_lt_u32_e32 vcc, v2, v6
	s_and_saveexec_b64 s[14:15], vcc
	s_cbranch_execz .LBB0_172
	s_add_u32 s12, s30, 0x200
	s_addc_u32 s13, s31, 0
	s_mov_b32 s3, 1
	s_branch .LBB0_165

; __device__ __forceinline__ unsigned xb_ld(unsigned* p)              { return __hip_atomic_load(p, __ATOMIC_RELAXED, __HIP_MEMORY_SCOPE_AGENT); }
; #define XB_SPIN(cond, bar) do { unsigned _sp = 0; while (cond) { __builtin_amdgcn_s_sleep(1); \
;     if ((++_sp & 255u) == 0u) { if (xb_ld(&(bar)[XB_TMO])) break; if (_sp > XB_SPIN_CAP) { atomicAdd(&(bar)[XB_TMO], 1u); break; } } } } while (0)
; __device__ __forceinline__ void xcd_barrier(const XcdBarrier& b) {
;     ...
;             else XB_SPIN(xb_ld(&bar[XB_TOPGEN]) == tg, bar);
.LBB0_167:
	global_load_dword v2, v1, s[10:11] offset:-256 sc1
	s_add_i32 s3, s3, 1
	s_mov_b64 s[40:41], -1
	s_waitcnt vmcnt(0)
	v_cmp_ge_u32_e32 vcc, v2, v6
	s_orn2_b64 s[44:45], vcc, exec
	s_branch .LBB0_164

; __device__ __forceinline__ unsigned xb_ld(unsigned* p)              { return __hip_atomic_load(p, __ATOMIC_RELAXED, __HIP_MEMORY_SCOPE_AGENT); }
; __device__ __forceinline__ unsigned xb_add(unsigned* p, unsigned v) { return __hip_atomic_fetch_add(p, v, __ATOMIC_RELAXED, __HIP_MEMORY_SCOPE_AGENT); }
; #define XB_SPIN(cond, bar) do { unsigned _sp = 0; while (cond) { __builtin_amdgcn_s_sleep(1); \
;     if ((++_sp & 255u) == 0u) { if (xb_ld(&(bar)[XB_TMO])) break; if (_sp > XB_SPIN_CAP) { atomicAdd(&(bar)[XB_TMO], 1u); break; } } } } while (0)
; __device__ __forceinline__ void xcd_barrier(const XcdBarrier& b) {
;     ...
;         const unsigned old = xb_add(&bar[XB_XSUB(b.x)], 1u);
;         const unsigned gen = old / nloc;
;         if (old + 1u == (gen + 1u) * nloc) {
;             __builtin_amdgcn_fence(__ATOMIC_RELEASE, "agent");
;             asm volatile("s_waitcnt vmcnt(0)" ::: "memory");
;             const unsigned og = xb_add(&bar[XB_TOP], 1u);
;             const unsigned tg = og / nx;
;             if (og + 1u == (tg + 1u) * nx) xb_add(&bar[XB_TOPGEN], 1u);
;             else XB_SPIN(xb_ld(&bar[XB_TOPGEN]) == tg, bar);
;             __builtin_amdgcn_fence(__ATOMIC_ACQUIRE, "agent");
;             xb_add(&bar[XB_XGEN(b.x)], 1u);
;             asm volatile("s_waitcnt vmcnt(0)" ::: "memory");
;         } else {
;             XB_SPIN(xb_ld(&bar[XB_XGEN(b.x)]) == gen, bar);
;             __builtin_amdgcn_fence(__ATOMIC_ACQUIRE, "agent");
;             asm volatile("s_waitcnt vmcnt(0)" ::: "memory");
.LBB0_247:
	s_or_b64 exec, exec, s[8:9]
	v_cvt_f32_u32_e32 v5, v3
	s_waitcnt vmcnt(0)
	v_readfirstlane_b32 s6, v4
	v_sub_u32_e32 v4, 0, v3
	v_rcp_iflag_f32_e32 v5, v5
	v_add_u32_e32 v6, s6, v2
	v_mul_f32_e32 v5, 0x4f7ffffe, v5
	v_cvt_u32_f32_e32 v5, v5
	v_mul_lo_u32 v2, v4, v5
	v_mul_hi_u32 v2, v5, v2
	v_add_u32_e32 v2, v5, v2
	v_mul_hi_u32 v2, v6, v2
	v_mul_lo_u32 v4, v2, v3
	v_sub_u32_e32 v4, v6, v4
	v_add_u32_e32 v5, 1, v2
	v_cmp_ge_u32_e32 vcc, v4, v3
	s_nop 1
	v_cndmask_b32_e32 v2, v2, v5, vcc
	v_sub_u32_e32 v5, v4, v3
	v_cndmask_b32_e32 v4, v4, v5, vcc
	v_add_u32_e32 v5, 1, v2
	v_cmp_ge_u32_e32 vcc, v4, v3
	v_add_u32_e32 v4, 1, v6
	s_nop 0
	v_cndmask_b32_e32 v2, v2, v5, vcc
	v_mul_lo_u32 v5, v3, v2
	v_add_u32_e32 v3, v5, v3
	v_cmp_ne_u32_e32 vcc, v4, v3
	s_and_saveexec_b64 s[6:7], vcc
	s_xor_b64 s[6:7], exec, s[6:7]
	s_cbranch_execz .LBB0_261
	s_waitcnt lgkmcnt(0)
	v_add_u32_e32 v4, 1, v2
	v_mul_lo_u32 v4, v4, v1
	v_mov_b32_e32 v1, 0x3400
	global_load_dword v1, v1, s[30:31] sc1
	s_add_u32 s10, s30, 0x3400
	s_addc_u32 s11, s31, 0
	s_waitcnt vmcnt(0)
	v_cmp_lt_u32_e32 vcc, v1, v4
	s_and_saveexec_b64 s[8:9], vcc
	s_cbranch_execz .LBB0_260
	s_mov_b32 s33, 1
	s_mov_b64 s[12:13], 0
	v_mov_b32_e32 v1, 0
	s_branch .LBB0_251

; __device__ __forceinline__ unsigned xb_ld(unsigned* p)              { return __hip_atomic_load(p, __ATOMIC_RELAXED, __HIP_MEMORY_SCOPE_AGENT); }
; #define XB_SPIN(cond, bar) do { unsigned _sp = 0; while (cond) { __builtin_amdgcn_s_sleep(1); \
;     if ((++_sp & 255u) == 0u) { if (xb_ld(&(bar)[XB_TMO])) break; if (_sp > XB_SPIN_CAP) { atomicAdd(&(bar)[XB_TMO], 1u); break; } } } } while (0)
; __device__ __forceinline__ void xcd_barrier(const XcdBarrier& b) {
;     ...
;             XB_SPIN(xb_ld(&bar[XB_XGEN(b.x)]) == gen, bar);
.LBB0_253:
	global_load_dword v3, v1, s[10:11] sc1
	s_add_i32 s33, s33, 1
	s_mov_b64 s[38:39], -1
	s_waitcnt vmcnt(0)
	v_cmp_ge_u32_e32 vcc, v3, v4
	s_orn2_b64 s[16:17], vcc, exec
	s_branch .LBB0_250

; __device__ __forceinline__ unsigned xb_ld(unsigned* p)              { return __hip_atomic_load(p, __ATOMIC_RELAXED, __HIP_MEMORY_SCOPE_AGENT); }
; __device__ __forceinline__ unsigned xb_add(unsigned* p, unsigned v) { return __hip_atomic_fetch_add(p, v, __ATOMIC_RELAXED, __HIP_MEMORY_SCOPE_AGENT); }
; #define XB_SPIN(cond, bar) do { unsigned _sp = 0; while (cond) { __builtin_amdgcn_s_sleep(1); \
;     if ((++_sp & 255u) == 0u) { if (xb_ld(&(bar)[XB_TMO])) break; if (_sp > XB_SPIN_CAP) { atomicAdd(&(bar)[XB_TMO], 1u); break; } } } } while (0)
; __device__ __forceinline__ void xcd_barrier(const XcdBarrier& b) {
;     ...
;             const unsigned og = xb_add(&bar[XB_TOP], 1u);
;             const unsigned tg = og / nx;
;             if (og + 1u == (tg + 1u) * nx) xb_add(&bar[XB_TOPGEN], 1u);
;             else XB_SPIN(xb_ld(&bar[XB_TOPGEN]) == tg, bar);
;             __builtin_amdgcn_fence(__ATOMIC_ACQUIRE, "agent");
.LBB0_264:
	s_or_b64 exec, exec, s[10:11]
	v_cvt_f32_u32_e32 v4, v1
	s_waitcnt vmcnt(0)
	v_readfirstlane_b32 s8, v3
	s_add_u32 s10, s30, 0x3500
	s_addc_u32 s11, s31, 0
	v_rcp_iflag_f32_e32 v4, v4
	v_add_u32_e32 v2, s8, v2
	v_add_u32_e32 v5, 1, v2
	s_mov_b64 s[12:13], -1
	v_mul_f32_e32 v3, 0x4f7ffffe, v4
	v_cvt_u32_f32_e32 v3, v3
	v_sub_u32_e32 v4, 0, v1
	v_mul_lo_u32 v4, v4, v3
	v_mul_hi_u32 v4, v3, v4
	v_add_u32_e32 v3, v3, v4
	v_mul_hi_u32 v3, v2, v3
	v_mul_lo_u32 v4, v3, v1
	v_sub_u32_e32 v2, v2, v4
	v_add_u32_e32 v6, 1, v3
	v_cmp_ge_u32_e32 vcc, v2, v1
	v_sub_u32_e32 v4, v2, v1
	s_nop 0
	v_cndmask_b32_e32 v3, v3, v6, vcc
	v_cndmask_b32_e32 v2, v2, v4, vcc
	v_add_u32_e32 v4, 1, v3
	v_cmp_ge_u32_e32 vcc, v2, v1
	s_nop 1
	v_cndmask_b32_e32 v4, v3, v4, vcc
	v_mul_lo_u32 v2, v1, v4
	v_add_u32_e32 v1, v2, v1
	v_mov_b32_e32 v6, v1
	v_cmp_ne_u32_e32 vcc, v5, v1
	v_mov_b64_e32 v[2:3], s[10:11]
	s_and_saveexec_b64 s[8:9], vcc
	s_cbranch_execz .LBB0_276
	v_mov_b32_e32 v1, 0
	global_load_dword v2, v1, s[10:11] offset:-256 sc1
	s_mov_b64 s[16:17], 0
	s_waitcnt vmcnt(0)
	v_cmp_lt_u32_e32 vcc, v2, v6
	s_and_saveexec_b64 s[14:15], vcc
	s_cbranch_execz .LBB0_275
	s_add_u32 s12, s30, 0x200
	s_addc_u32 s13, s31, 0
	s_mov_b32 s33, 1
	s_branch .LBB0_268

; __device__ __forceinline__ unsigned xb_ld(unsigned* p)              { return __hip_atomic_load(p, __ATOMIC_RELAXED, __HIP_MEMORY_SCOPE_AGENT); }
; #define XB_SPIN(cond, bar) do { unsigned _sp = 0; while (cond) { __builtin_amdgcn_s_sleep(1); \
;     if ((++_sp & 255u) == 0u) { if (xb_ld(&(bar)[XB_TMO])) break; if (_sp > XB_SPIN_CAP) { atomicAdd(&(bar)[XB_TMO], 1u); break; } } } } while (0)
; __device__ __forceinline__ void xcd_barrier(const XcdBarrier& b) {
;     ...
;             else XB_SPIN(xb_ld(&bar[XB_TOPGEN]) == tg, bar);
.LBB0_270:
	global_load_dword v2, v1, s[10:11] offset:-256 sc1
	s_add_i32 s33, s33, 1
	s_mov_b64 s[40:41], -1
	s_waitcnt vmcnt(0)
	v_cmp_ge_u32_e32 vcc, v2, v6
	s_orn2_b64 s[44:45], vcc, exec
	s_branch .LBB0_267

; __device__ __forceinline__ unsigned xb_ld(unsigned* p)              { return __hip_atomic_load(p, __ATOMIC_RELAXED, __HIP_MEMORY_SCOPE_AGENT); }
; #define XB_SPIN(cond, bar) do { unsigned _sp = 0; while (cond) { __builtin_amdgcn_s_sleep(1); \
;     if ((++_sp & 255u) == 0u) { if (xb_ld(&(bar)[XB_TMO])) break; if (_sp > XB_SPIN_CAP) { atomicAdd(&(bar)[XB_TMO], 1u); break; } } } } while (0)
; __device__ __forceinline__ void xcd_barrier(const XcdBarrier& b) {
;     ...
;             XB_SPIN(xb_ld(&bar[XB_XGEN(b.x)]) == gen, bar);
.LBB0_402:
	global_load_dword v3, v1, s[10:11] sc1
	s_add_i32 s33, s33, 1
	s_mov_b64 s[20:21], -1
	s_waitcnt vmcnt(0)
	v_cmp_ge_u32_e32 vcc, v3, v4
	s_orn2_b64 s[16:17], vcc, exec
	s_branch .LBB0_399

; __device__ __forceinline__ unsigned xb_ld(unsigned* p)              { return __hip_atomic_load(p, __ATOMIC_RELAXED, __HIP_MEMORY_SCOPE_AGENT); }
; #define XB_SPIN(cond, bar) do { unsigned _sp = 0; while (cond) { __builtin_amdgcn_s_sleep(1); \
;     if ((++_sp & 255u) == 0u) { if (xb_ld(&(bar)[XB_TMO])) break; if (_sp > XB_SPIN_CAP) { atomicAdd(&(bar)[XB_TMO], 1u); break; } } } } while (0)
; __device__ __forceinline__ void xcd_barrier(const XcdBarrier& b) {
;     ...
;             else XB_SPIN(xb_ld(&bar[XB_TOPGEN]) == tg, bar);
.LBB0_419:
	global_load_dword v2, v1, s[10:11] offset:-256 sc1
	s_add_i32 s33, s33, 1
	s_mov_b64 s[22:23], -1
	s_waitcnt vmcnt(0)
	v_cmp_ge_u32_e32 vcc, v2, v6
	s_orn2_b64 s[40:41], vcc, exec
	s_branch .LBB0_416

; __device__ __forceinline__ unsigned xb_ld(unsigned* p)              { return __hip_atomic_load(p, __ATOMIC_RELAXED, __HIP_MEMORY_SCOPE_AGENT); }
; __device__ __forceinline__ unsigned xb_add(unsigned* p, unsigned v) { return __hip_atomic_fetch_add(p, v, __ATOMIC_RELAXED, __HIP_MEMORY_SCOPE_AGENT); }
; #define XB_SPIN(cond, bar) do { unsigned _sp = 0; while (cond) { __builtin_amdgcn_s_sleep(1); \
;     if ((++_sp & 255u) == 0u) { if (xb_ld(&(bar)[XB_TMO])) break; if (_sp > XB_SPIN_CAP) { atomicAdd(&(bar)[XB_TMO], 1u); break; } } } } while (0)
; __device__ __forceinline__ void xcd_barrier(const XcdBarrier& b) {
;     ...
;         const unsigned old = xb_add(&bar[XB_XSUB(b.x)], 1u);
;         const unsigned gen = old / nloc;
;         if (old + 1u == (gen + 1u) * nloc) {
;             __builtin_amdgcn_fence(__ATOMIC_RELEASE, "agent");
;             asm volatile("s_waitcnt vmcnt(0)" ::: "memory");
;             const unsigned og = xb_add(&bar[XB_TOP], 1u);
;             const unsigned tg = og / nx;
;             if (og + 1u == (tg + 1u) * nx) xb_add(&bar[XB_TOPGEN], 1u);
;             else XB_SPIN(xb_ld(&bar[XB_TOPGEN]) == tg, bar);
;             __builtin_amdgcn_fence(__ATOMIC_ACQUIRE, "agent");
;             xb_add(&bar[XB_XGEN(b.x)], 1u);
;             asm volatile("s_waitcnt vmcnt(0)" ::: "memory");
;         } else {
;             XB_SPIN(xb_ld(&bar[XB_XGEN(b.x)]) == gen, bar);
;             __builtin_amdgcn_fence(__ATOMIC_ACQUIRE, "agent");
;             asm volatile("s_waitcnt vmcnt(0)" ::: "memory");
.LBB0_737:
	s_or_b64 exec, exec, s[8:9]
	v_cvt_f32_u32_e32 v5, v3
	s_waitcnt vmcnt(0)
	v_readfirstlane_b32 s6, v4
	v_sub_u32_e32 v4, 0, v3
	v_rcp_iflag_f32_e32 v5, v5
	v_add_u32_e32 v6, s6, v2
	v_mul_f32_e32 v5, 0x4f7ffffe, v5
	v_cvt_u32_f32_e32 v5, v5
	v_mul_lo_u32 v2, v4, v5
	v_mul_hi_u32 v2, v5, v2
	v_add_u32_e32 v2, v5, v2
	v_mul_hi_u32 v2, v6, v2
	v_mul_lo_u32 v4, v2, v3
	v_sub_u32_e32 v4, v6, v4
	v_add_u32_e32 v5, 1, v2
	v_cmp_ge_u32_e32 vcc, v4, v3
	s_nop 1
	v_cndmask_b32_e32 v2, v2, v5, vcc
	v_sub_u32_e32 v5, v4, v3
	v_cndmask_b32_e32 v4, v4, v5, vcc
	v_add_u32_e32 v5, 1, v2
	v_cmp_ge_u32_e32 vcc, v4, v3
	v_add_u32_e32 v4, 1, v6
	s_nop 0
	v_cndmask_b32_e32 v2, v2, v5, vcc
	v_mul_lo_u32 v5, v3, v2
	v_add_u32_e32 v3, v5, v3
	v_cmp_ne_u32_e32 vcc, v4, v3
	s_and_saveexec_b64 s[6:7], vcc
	s_xor_b64 s[6:7], exec, s[6:7]
	s_cbranch_execz .LBB0_751
	s_waitcnt lgkmcnt(0)
	v_add_u32_e32 v4, 1, v2
	v_mul_lo_u32 v4, v4, v1
	v_mov_b32_e32 v1, 0x3400
	global_load_dword v1, v1, s[30:31] sc1
	s_add_u32 s12, s30, 0x3400
	s_addc_u32 s13, s31, 0
	s_waitcnt vmcnt(0)
	v_cmp_lt_u32_e32 vcc, v1, v4
	s_and_saveexec_b64 s[8:9], vcc
	s_cbranch_execz .LBB0_750
	s_mov_b32 s33, 1
	s_mov_b64 s[14:15], 0
	v_mov_b32_e32 v1, 0
	s_branch .LBB0_741

; __device__ __forceinline__ unsigned xb_ld(unsigned* p)              { return __hip_atomic_load(p, __ATOMIC_RELAXED, __HIP_MEMORY_SCOPE_AGENT); }
; #define XB_SPIN(cond, bar) do { unsigned _sp = 0; while (cond) { __builtin_amdgcn_s_sleep(1); \
;     if ((++_sp & 255u) == 0u) { if (xb_ld(&(bar)[XB_TMO])) break; if (_sp > XB_SPIN_CAP) { atomicAdd(&(bar)[XB_TMO], 1u); break; } } } } while (0)
; __device__ __forceinline__ void xcd_barrier(const XcdBarrier& b) {
;     ...
;             XB_SPIN(xb_ld(&bar[XB_XGEN(b.x)]) == gen, bar);
.LBB0_743:
	global_load_dword v3, v1, s[12:13] sc1
	s_add_i32 s33, s33, 1
	s_mov_b64 s[22:23], -1
	s_waitcnt vmcnt(0)
	v_cmp_ge_u32_e32 vcc, v3, v4
	s_orn2_b64 s[20:21], vcc, exec
	s_branch .LBB0_740

; __device__ __forceinline__ unsigned xb_ld(unsigned* p)              { return __hip_atomic_load(p, __ATOMIC_RELAXED, __HIP_MEMORY_SCOPE_AGENT); }
; __device__ __forceinline__ unsigned xb_add(unsigned* p, unsigned v) { return __hip_atomic_fetch_add(p, v, __ATOMIC_RELAXED, __HIP_MEMORY_SCOPE_AGENT); }
; #define XB_SPIN(cond, bar) do { unsigned _sp = 0; while (cond) { __builtin_amdgcn_s_sleep(1); \
;     if ((++_sp & 255u) == 0u) { if (xb_ld(&(bar)[XB_TMO])) break; if (_sp > XB_SPIN_CAP) { atomicAdd(&(bar)[XB_TMO], 1u); break; } } } } while (0)
; __device__ __forceinline__ void xcd_barrier(const XcdBarrier& b) {
;     ...
;             const unsigned og = xb_add(&bar[XB_TOP], 1u);
;             const unsigned tg = og / nx;
;             if (og + 1u == (tg + 1u) * nx) xb_add(&bar[XB_TOPGEN], 1u);
;             else XB_SPIN(xb_ld(&bar[XB_TOPGEN]) == tg, bar);
;             __builtin_amdgcn_fence(__ATOMIC_ACQUIRE, "agent");
.LBB0_754:
	s_or_b64 exec, exec, s[12:13]
	v_cvt_f32_u32_e32 v4, v1
	s_waitcnt vmcnt(0)
	v_readfirstlane_b32 s8, v3
	s_add_u32 s12, s30, 0x3500
	s_addc_u32 s13, s31, 0
	v_rcp_iflag_f32_e32 v4, v4
	v_add_u32_e32 v2, s8, v2
	v_add_u32_e32 v5, 1, v2
	s_mov_b64 s[14:15], -1
	v_mul_f32_e32 v3, 0x4f7ffffe, v4
	v_cvt_u32_f32_e32 v3, v3
	v_sub_u32_e32 v4, 0, v1
	v_mul_lo_u32 v4, v4, v3
	v_mul_hi_u32 v4, v3, v4
	v_add_u32_e32 v3, v3, v4
	v_mul_hi_u32 v3, v2, v3
	v_mul_lo_u32 v4, v3, v1
	v_sub_u32_e32 v2, v2, v4
	v_add_u32_e32 v6, 1, v3
	v_cmp_ge_u32_e32 vcc, v2, v1
	v_sub_u32_e32 v4, v2, v1
	s_nop 0
	v_cndmask_b32_e32 v3, v3, v6, vcc
	v_cndmask_b32_e32 v2, v2, v4, vcc
	v_add_u32_e32 v4, 1, v3
	v_cmp_ge_u32_e32 vcc, v2, v1
	s_nop 1
	v_cndmask_b32_e32 v4, v3, v4, vcc
	v_mul_lo_u32 v2, v1, v4
	v_add_u32_e32 v1, v2, v1
	v_mov_b32_e32 v6, v1
	v_cmp_ne_u32_e32 vcc, v5, v1
	v_mov_b64_e32 v[2:3], s[12:13]
	s_and_saveexec_b64 s[8:9], vcc
	s_cbranch_execz .LBB0_766
	v_mov_b32_e32 v1, 0
	global_load_dword v2, v1, s[12:13] offset:-256 sc1
	s_mov_b64 s[20:21], 0
	s_waitcnt vmcnt(0)
	v_cmp_lt_u32_e32 vcc, v2, v6
	s_and_saveexec_b64 s[16:17], vcc
	s_cbranch_execz .LBB0_765
	s_add_u32 s14, s30, 0x200
	s_addc_u32 s15, s31, 0
	s_mov_b32 s33, 1
	s_branch .LBB0_758

; __device__ __forceinline__ unsigned xb_ld(unsigned* p)              { return __hip_atomic_load(p, __ATOMIC_RELAXED, __HIP_MEMORY_SCOPE_AGENT); }
; __device__ __forceinline__ unsigned xb_add(unsigned* p, unsigned v) { return __hip_atomic_fetch_add(p, v, __ATOMIC_RELAXED, __HIP_MEMORY_SCOPE_AGENT); }
; #define XB_SPIN(cond, bar) do { unsigned _sp = 0; while (cond) { __builtin_amdgcn_s_sleep(1); \
;     if ((++_sp & 255u) == 0u) { if (xb_ld(&(bar)[XB_TMO])) break; if (_sp > XB_SPIN_CAP) { atomicAdd(&(bar)[XB_TMO], 1u); break; } } } } while (0)
; __device__ __forceinline__ void xcd_barrier(const XcdBarrier& b) {
;     ...
;             const unsigned og = xb_add(&bar[XB_TOP], 1u);
;             const unsigned tg = og / nx;
;             if (og + 1u == (tg + 1u) * nx) xb_add(&bar[XB_TOPGEN], 1u);
;             else XB_SPIN(xb_ld(&bar[XB_TOPGEN]) == tg, bar);
;             __builtin_amdgcn_fence(__ATOMIC_ACQUIRE, "agent");
.LBB0_760:
	global_load_dword v2, v1, s[12:13] offset:-256 sc1
	s_add_i32 s33, s33, 1
	s_mov_b64 s[38:39], -1
	s_waitcnt vmcnt(0)
	v_cmp_ge_u32_e32 vcc, v2, v6
	s_orn2_b64 s[42:43], vcc, exec
	s_branch .LBB0_757

; __device__ __forceinline__ unsigned xb_ld(unsigned* p)              { return __hip_atomic_load(p, __ATOMIC_RELAXED, __HIP_MEMORY_SCOPE_AGENT); }
; __device__ __forceinline__ unsigned xb_add(unsigned* p, unsigned v) { return __hip_atomic_fetch_add(p, v, __ATOMIC_RELAXED, __HIP_MEMORY_SCOPE_AGENT); }
; #define XB_SPIN(cond, bar) do { unsigned _sp = 0; while (cond) { __builtin_amdgcn_s_sleep(1); \
;     if ((++_sp & 255u) == 0u) { if (xb_ld(&(bar)[XB_TMO])) break; if (_sp > XB_SPIN_CAP) { atomicAdd(&(bar)[XB_TMO], 1u); break; } } } } while (0)
; __device__ __forceinline__ void xcd_barrier(const XcdBarrier& b) {
;     ...
;         const unsigned old = xb_add(&bar[XB_XSUB(b.x)], 1u);
;         const unsigned gen = old / nloc;
;         if (old + 1u == (gen + 1u) * nloc) {
;             __builtin_amdgcn_fence(__ATOMIC_RELEASE, "agent");
;             asm volatile("s_waitcnt vmcnt(0)" ::: "memory");
;             const unsigned og = xb_add(&bar[XB_TOP], 1u);
;             const unsigned tg = og / nx;
;             if (og + 1u == (tg + 1u) * nx) xb_add(&bar[XB_TOPGEN], 1u);
;             else XB_SPIN(xb_ld(&bar[XB_TOPGEN]) == tg, bar);
;             __builtin_amdgcn_fence(__ATOMIC_ACQUIRE, "agent");
;             xb_add(&bar[XB_XGEN(b.x)], 1u);
;             asm volatile("s_waitcnt vmcnt(0)" ::: "memory");
;         } else {
;             XB_SPIN(xb_ld(&bar[XB_XGEN(b.x)]) == gen, bar);
;             __builtin_amdgcn_fence(__ATOMIC_ACQUIRE, "agent");
;             asm volatile("s_waitcnt vmcnt(0)" ::: "memory");
.LBB0_820:
	s_or_b64 exec, exec, s[8:9]
	v_cvt_f32_u32_e32 v5, v3
	s_waitcnt vmcnt(0)
	v_readfirstlane_b32 s6, v4
	v_sub_u32_e32 v4, 0, v3
	v_rcp_iflag_f32_e32 v5, v5
	v_add_u32_e32 v6, s6, v2
	v_mul_f32_e32 v5, 0x4f7ffffe, v5
	v_cvt_u32_f32_e32 v5, v5
	v_mul_lo_u32 v2, v4, v5
	v_mul_hi_u32 v2, v5, v2
	v_add_u32_e32 v2, v5, v2
	v_mul_hi_u32 v2, v6, v2
	v_mul_lo_u32 v4, v2, v3
	v_sub_u32_e32 v4, v6, v4
	v_add_u32_e32 v5, 1, v2
	v_cmp_ge_u32_e32 vcc, v4, v3
	s_nop 1
	v_cndmask_b32_e32 v2, v2, v5, vcc
	v_sub_u32_e32 v5, v4, v3
	v_cndmask_b32_e32 v4, v4, v5, vcc
	v_add_u32_e32 v5, 1, v2
	v_cmp_ge_u32_e32 vcc, v4, v3
	v_add_u32_e32 v4, 1, v6
	s_nop 0
	v_cndmask_b32_e32 v2, v2, v5, vcc
	v_mul_lo_u32 v5, v3, v2
	v_add_u32_e32 v3, v5, v3
	v_cmp_ne_u32_e32 vcc, v4, v3
	s_and_saveexec_b64 s[6:7], vcc
	s_xor_b64 s[6:7], exec, s[6:7]
	s_cbranch_execz .LBB0_834
	s_waitcnt lgkmcnt(0)
	v_add_u32_e32 v4, 1, v2
	v_mul_lo_u32 v4, v4, v1
	v_mov_b32_e32 v1, 0x3400
	global_load_dword v1, v1, s[30:31] sc1
	s_add_u32 s10, s30, 0x3400
	s_addc_u32 s11, s31, 0
	s_waitcnt vmcnt(0)
	v_cmp_lt_u32_e32 vcc, v1, v4
	s_and_saveexec_b64 s[8:9], vcc
	s_cbranch_execz .LBB0_833
	s_mov_b32 s24, 1
	s_mov_b64 s[12:13], 0
	v_mov_b32_e32 v1, 0
	s_branch .LBB0_824

; __device__ __forceinline__ unsigned xb_ld(unsigned* p)              { return __hip_atomic_load(p, __ATOMIC_RELAXED, __HIP_MEMORY_SCOPE_AGENT); }
; #define XB_SPIN(cond, bar) do { unsigned _sp = 0; while (cond) { __builtin_amdgcn_s_sleep(1); \
;     if ((++_sp & 255u) == 0u) { if (xb_ld(&(bar)[XB_TMO])) break; if (_sp > XB_SPIN_CAP) { atomicAdd(&(bar)[XB_TMO], 1u); break; } } } } while (0)
; __device__ __forceinline__ void xcd_barrier(const XcdBarrier& b) {
;     ...
;         } else {
;             XB_SPIN(xb_ld(&bar[XB_XGEN(b.x)]) == gen, bar);
;             __builtin_amdgcn_fence(__ATOMIC_ACQUIRE, "agent");
;             asm volatile("s_waitcnt vmcnt(0)" ::: "memory");
.LBB0_826:
	global_load_dword v3, v1, s[10:11] sc1
	s_add_i32 s24, s24, 1
	s_mov_b64 s[20:21], -1
	s_waitcnt vmcnt(0)
	v_cmp_ge_u32_e32 vcc, v3, v4
	s_orn2_b64 s[16:17], vcc, exec
	s_branch .LBB0_823

; __device__ __forceinline__ unsigned xb_ld(unsigned* p)              { return __hip_atomic_load(p, __ATOMIC_RELAXED, __HIP_MEMORY_SCOPE_AGENT); }
; __device__ __forceinline__ unsigned xb_add(unsigned* p, unsigned v) { return __hip_atomic_fetch_add(p, v, __ATOMIC_RELAXED, __HIP_MEMORY_SCOPE_AGENT); }
; #define XB_SPIN(cond, bar) do { unsigned _sp = 0; while (cond) { __builtin_amdgcn_s_sleep(1); \
;     if ((++_sp & 255u) == 0u) { if (xb_ld(&(bar)[XB_TMO])) break; if (_sp > XB_SPIN_CAP) { atomicAdd(&(bar)[XB_TMO], 1u); break; } } } } while (0)
; __device__ __forceinline__ void xcd_barrier(const XcdBarrier& b) {
;     ...
;             if (og + 1u == (tg + 1u) * nx) xb_add(&bar[XB_TOPGEN], 1u);
;             else XB_SPIN(xb_ld(&bar[XB_TOPGEN]) == tg, bar);
;             __builtin_amdgcn_fence(__ATOMIC_ACQUIRE, "agent");
.LBB0_843:
	global_load_dword v2, v1, s[10:11] offset:-256 sc1
	s_add_i32 s33, s33, 1
	s_mov_b64 s[22:23], -1
	s_waitcnt vmcnt(0)
	v_cmp_ge_u32_e32 vcc, v2, v6
	s_orn2_b64 s[38:39], vcc, exec
	s_branch .LBB0_840

; __device__ __forceinline__ unsigned xb_ld(unsigned* p)              { return __hip_atomic_load(p, __ATOMIC_RELAXED, __HIP_MEMORY_SCOPE_AGENT); }
; __device__ __forceinline__ unsigned xb_add(unsigned* p, unsigned v) { return __hip_atomic_fetch_add(p, v, __ATOMIC_RELAXED, __HIP_MEMORY_SCOPE_AGENT); }
; #define XB_SPIN(cond, bar) do { unsigned _sp = 0; while (cond) { __builtin_amdgcn_s_sleep(1); \
;     if ((++_sp & 255u) == 0u) { if (xb_ld(&(bar)[XB_TMO])) break; if (_sp > XB_SPIN_CAP) { atomicAdd(&(bar)[XB_TMO], 1u); break; } } } } while (0)
; __device__ __forceinline__ void xcd_barrier(const XcdBarrier& b) {
;     ...
;         const unsigned old = xb_add(&bar[XB_XSUB(b.x)], 1u);
;         const unsigned gen = old / nloc;
;         if (old + 1u == (gen + 1u) * nloc) {
;             __builtin_amdgcn_fence(__ATOMIC_RELEASE, "agent");
;             asm volatile("s_waitcnt vmcnt(0)" ::: "memory");
;             const unsigned og = xb_add(&bar[XB_TOP], 1u);
;             const unsigned tg = og / nx;
;             if (og + 1u == (tg + 1u) * nx) xb_add(&bar[XB_TOPGEN], 1u);
;             else XB_SPIN(xb_ld(&bar[XB_TOPGEN]) == tg, bar);
;             __builtin_amdgcn_fence(__ATOMIC_ACQUIRE, "agent");
;             xb_add(&bar[XB_XGEN(b.x)], 1u);
;             asm volatile("s_waitcnt vmcnt(0)" ::: "memory");
;         } else {
;             XB_SPIN(xb_ld(&bar[XB_XGEN(b.x)]) == gen, bar);
;             __builtin_amdgcn_fence(__ATOMIC_ACQUIRE, "agent");
;             asm volatile("s_waitcnt vmcnt(0)" ::: "memory");
.LBB0_913:
	s_or_b64 exec, exec, s[14:15]
	v_cvt_f32_u32_e32 v5, v3
	s_waitcnt vmcnt(0)
	v_readfirstlane_b32 s8, v4
	v_sub_u32_e32 v4, 0, v3
	v_rcp_iflag_f32_e32 v5, v5
	v_add_u32_e32 v6, s8, v2
	v_mul_f32_e32 v5, 0x4f7ffffe, v5
	v_cvt_u32_f32_e32 v5, v5
	v_mul_lo_u32 v2, v4, v5
	v_mul_hi_u32 v2, v5, v2
	v_add_u32_e32 v2, v5, v2
	v_mul_hi_u32 v2, v6, v2
	v_mul_lo_u32 v4, v2, v3
	v_sub_u32_e32 v4, v6, v4
	v_add_u32_e32 v5, 1, v2
	v_cmp_ge_u32_e32 vcc, v4, v3
	s_nop 1
	v_cndmask_b32_e32 v2, v2, v5, vcc
	v_sub_u32_e32 v5, v4, v3
	v_cndmask_b32_e32 v4, v4, v5, vcc
	v_add_u32_e32 v5, 1, v2
	v_cmp_ge_u32_e32 vcc, v4, v3
	v_add_u32_e32 v4, 1, v6
	s_nop 0
	v_cndmask_b32_e32 v2, v2, v5, vcc
	v_mul_lo_u32 v5, v3, v2
	v_add_u32_e32 v3, v5, v3
	v_cmp_ne_u32_e32 vcc, v4, v3
	s_and_saveexec_b64 s[8:9], vcc
	s_xor_b64 s[8:9], exec, s[8:9]
	s_cbranch_execz .LBB0_927
	s_waitcnt lgkmcnt(0)
	v_add_u32_e32 v4, 1, v2
	v_mul_lo_u32 v4, v4, v1
	v_mov_b32_e32 v1, 0x3400
	global_load_dword v1, v1, s[30:31] sc1
	s_add_u32 s16, s30, 0x3400
	s_addc_u32 s17, s31, 0
	s_waitcnt vmcnt(0)
	v_cmp_lt_u32_e32 vcc, v1, v4
	s_and_saveexec_b64 s[14:15], vcc
	s_cbranch_execz .LBB0_926
	s_mov_b32 s33, 1
	s_mov_b64 s[20:21], 0
	v_mov_b32_e32 v1, 0
	s_branch .LBB0_917

; __device__ __forceinline__ unsigned xb_ld(unsigned* p)              { return __hip_atomic_load(p, __ATOMIC_RELAXED, __HIP_MEMORY_SCOPE_AGENT); }
; #define XB_SPIN(cond, bar) do { unsigned _sp = 0; while (cond) { __builtin_amdgcn_s_sleep(1); \
;     if ((++_sp & 255u) == 0u) { if (xb_ld(&(bar)[XB_TMO])) break; if (_sp > XB_SPIN_CAP) { atomicAdd(&(bar)[XB_TMO], 1u); break; } } } } while (0)
; __device__ __forceinline__ void xcd_barrier(const XcdBarrier& b) {
;     ...
;         } else {
;             XB_SPIN(xb_ld(&bar[XB_XGEN(b.x)]) == gen, bar);
;             __builtin_amdgcn_fence(__ATOMIC_ACQUIRE, "agent");
;             asm volatile("s_waitcnt vmcnt(0)" ::: "memory");
.LBB0_919:
	global_load_dword v3, v1, s[16:17] sc1
	s_add_i32 s33, s33, 1
	s_mov_b64 s[38:39], -1
	s_waitcnt vmcnt(0)
	v_cmp_ge_u32_e32 vcc, v3, v4
	s_orn2_b64 s[24:25], vcc, exec
	s_branch .LBB0_916

; __device__ __forceinline__ unsigned xb_ld(unsigned* p)              { return __hip_atomic_load(p, __ATOMIC_RELAXED, __HIP_MEMORY_SCOPE_AGENT); }
; __device__ __forceinline__ unsigned xb_add(unsigned* p, unsigned v) { return __hip_atomic_fetch_add(p, v, __ATOMIC_RELAXED, __HIP_MEMORY_SCOPE_AGENT); }
; #define XB_SPIN(cond, bar) do { unsigned _sp = 0; while (cond) { __builtin_amdgcn_s_sleep(1); \
;     if ((++_sp & 255u) == 0u) { if (xb_ld(&(bar)[XB_TMO])) break; if (_sp > XB_SPIN_CAP) { atomicAdd(&(bar)[XB_TMO], 1u); break; } } } } while (0)
; __device__ __forceinline__ void xcd_barrier(const XcdBarrier& b) {
;     ...
;             const unsigned og = xb_add(&bar[XB_TOP], 1u);
;             const unsigned tg = og / nx;
;             if (og + 1u == (tg + 1u) * nx) xb_add(&bar[XB_TOPGEN], 1u);
;             else XB_SPIN(xb_ld(&bar[XB_TOPGEN]) == tg, bar);
;             __builtin_amdgcn_fence(__ATOMIC_ACQUIRE, "agent");
.LBB0_930:
	s_or_b64 exec, exec, s[16:17]
	v_cvt_f32_u32_e32 v4, v1
	s_waitcnt vmcnt(0)
	v_readfirstlane_b32 s14, v3
	s_add_u32 s16, s30, 0x3500
	s_addc_u32 s17, s31, 0
	v_rcp_iflag_f32_e32 v4, v4
	v_add_u32_e32 v2, s14, v2
	v_add_u32_e32 v5, 1, v2
	s_mov_b64 s[20:21], -1
	v_mul_f32_e32 v3, 0x4f7ffffe, v4
	v_cvt_u32_f32_e32 v3, v3
	v_sub_u32_e32 v4, 0, v1
	v_mul_lo_u32 v4, v4, v3
	v_mul_hi_u32 v4, v3, v4
	v_add_u32_e32 v3, v3, v4
	v_mul_hi_u32 v3, v2, v3
	v_mul_lo_u32 v4, v3, v1
	v_sub_u32_e32 v2, v2, v4
	v_add_u32_e32 v6, 1, v3
	v_cmp_ge_u32_e32 vcc, v2, v1
	v_sub_u32_e32 v4, v2, v1
	s_nop 0
	v_cndmask_b32_e32 v3, v3, v6, vcc
	v_cndmask_b32_e32 v2, v2, v4, vcc
	v_add_u32_e32 v4, 1, v3
	v_cmp_ge_u32_e32 vcc, v2, v1
	s_nop 1
	v_cndmask_b32_e32 v4, v3, v4, vcc
	v_mul_lo_u32 v2, v1, v4
	v_add_u32_e32 v1, v2, v1
	v_mov_b32_e32 v6, v1
	v_cmp_ne_u32_e32 vcc, v5, v1
	v_mov_b64_e32 v[2:3], s[16:17]
	s_and_saveexec_b64 s[14:15], vcc
	s_cbranch_execz .LBB0_942
	v_mov_b32_e32 v1, 0
	global_load_dword v2, v1, s[16:17] offset:-256 sc1
	s_mov_b64 s[24:25], 0
	s_waitcnt vmcnt(0)
	v_cmp_lt_u32_e32 vcc, v2, v6
	s_and_saveexec_b64 s[22:23], vcc
	s_cbranch_execz .LBB0_941
	s_add_u32 s20, s30, 0x200
	s_addc_u32 s21, s31, 0
	s_mov_b32 s33, 1
	s_branch .LBB0_934

; __device__ __forceinline__ unsigned xb_ld(unsigned* p)              { return __hip_atomic_load(p, __ATOMIC_RELAXED, __HIP_MEMORY_SCOPE_AGENT); }
; __device__ __forceinline__ unsigned xb_add(unsigned* p, unsigned v) { return __hip_atomic_fetch_add(p, v, __ATOMIC_RELAXED, __HIP_MEMORY_SCOPE_AGENT); }
; #define XB_SPIN(cond, bar) do { unsigned _sp = 0; while (cond) { __builtin_amdgcn_s_sleep(1); \
;     if ((++_sp & 255u) == 0u) { if (xb_ld(&(bar)[XB_TMO])) break; if (_sp > XB_SPIN_CAP) { atomicAdd(&(bar)[XB_TMO], 1u); break; } } } } while (0)
; __device__ __forceinline__ void xcd_barrier(const XcdBarrier& b) {
;     ...
;             if (og + 1u == (tg + 1u) * nx) xb_add(&bar[XB_TOPGEN], 1u);
;             else XB_SPIN(xb_ld(&bar[XB_TOPGEN]) == tg, bar);
;             __builtin_amdgcn_fence(__ATOMIC_ACQUIRE, "agent");
.LBB0_936:
	global_load_dword v2, v1, s[16:17] offset:-256 sc1
	s_add_i32 s33, s33, 1
	s_mov_b64 s[40:41], -1
	s_waitcnt vmcnt(0)
	v_cmp_ge_u32_e32 vcc, v2, v6
	s_orn2_b64 s[44:45], vcc, exec
	s_branch .LBB0_933

; __device__ __forceinline__ unsigned xb_ld(unsigned* p)              { return __hip_atomic_load(p, __ATOMIC_RELAXED, __HIP_MEMORY_SCOPE_AGENT); }
; #define XB_SPIN(cond, bar) do { unsigned _sp = 0; while (cond) { __builtin_amdgcn_s_sleep(1); \
;     if ((++_sp & 255u) == 0u) { if (xb_ld(&(bar)[XB_TMO])) break; if (_sp > XB_SPIN_CAP) { atomicAdd(&(bar)[XB_TMO], 1u); break; } } } } while (0)
; __device__ __forceinline__ void xcd_barrier(const XcdBarrier& b) {
;     ...
;         } else {
;             XB_SPIN(xb_ld(&bar[XB_XGEN(b.x)]) == gen, bar);
;             __builtin_amdgcn_fence(__ATOMIC_ACQUIRE, "agent");
;             asm volatile("s_waitcnt vmcnt(0)" ::: "memory");
.LBB0_1010:
	global_load_dword v3, v1, s[16:17] sc1
	s_add_i32 s33, s33, 1
	s_mov_b64 s[36:37], -1
	s_waitcnt vmcnt(0)
	v_cmp_ge_u32_e32 vcc, v3, v4
	s_orn2_b64 s[24:25], vcc, exec
	s_branch .LBB0_1007

; __device__ __forceinline__ unsigned xb_ld(unsigned* p)              { return __hip_atomic_load(p, __ATOMIC_RELAXED, __HIP_MEMORY_SCOPE_AGENT); }
; __device__ __forceinline__ unsigned xb_add(unsigned* p, unsigned v) { return __hip_atomic_fetch_add(p, v, __ATOMIC_RELAXED, __HIP_MEMORY_SCOPE_AGENT); }
; #define XB_SPIN(cond, bar) do { unsigned _sp = 0; while (cond) { __builtin_amdgcn_s_sleep(1); \
;     if ((++_sp & 255u) == 0u) { if (xb_ld(&(bar)[XB_TMO])) break; if (_sp > XB_SPIN_CAP) { atomicAdd(&(bar)[XB_TMO], 1u); break; } } } } while (0)
; __device__ __forceinline__ void xcd_barrier(const XcdBarrier& b) {
;     ...
;             if (og + 1u == (tg + 1u) * nx) xb_add(&bar[XB_TOPGEN], 1u);
;             else XB_SPIN(xb_ld(&bar[XB_TOPGEN]) == tg, bar);
;             __builtin_amdgcn_fence(__ATOMIC_ACQUIRE, "agent");
.LBB0_1027:
	global_load_dword v2, v1, s[16:17] offset:-256 sc1
	s_add_i32 s33, s33, 1
	s_mov_b64 s[38:39], -1
	s_waitcnt vmcnt(0)
	v_cmp_ge_u32_e32 vcc, v2, v6
	s_orn2_b64 s[42:43], vcc, exec
	s_branch .LBB0_1024

; __device__ __forceinline__ unsigned xb_ld(unsigned* p)              { return __hip_atomic_load(p, __ATOMIC_RELAXED, __HIP_MEMORY_SCOPE_AGENT); }
; __device__ __forceinline__ unsigned xb_add(unsigned* p, unsigned v) { return __hip_atomic_fetch_add(p, v, __ATOMIC_RELAXED, __HIP_MEMORY_SCOPE_AGENT); }
; #define XB_SPIN(cond, bar) do { unsigned _sp = 0; while (cond) { __builtin_amdgcn_s_sleep(1); \
;     if ((++_sp & 255u) == 0u) { if (xb_ld(&(bar)[XB_TMO])) break; if (_sp > XB_SPIN_CAP) { atomicAdd(&(bar)[XB_TMO], 1u); break; } } } } while (0)
; __device__ __forceinline__ void xcd_barrier(const XcdBarrier& b) {
;     ...
;         const unsigned old = xb_add(&bar[XB_XSUB(b.x)], 1u);
;         const unsigned gen = old / nloc;
;         if (old + 1u == (gen + 1u) * nloc) {
;             __builtin_amdgcn_fence(__ATOMIC_RELEASE, "agent");
;             asm volatile("s_waitcnt vmcnt(0)" ::: "memory");
;             const unsigned og = xb_add(&bar[XB_TOP], 1u);
;             const unsigned tg = og / nx;
;             if (og + 1u == (tg + 1u) * nx) xb_add(&bar[XB_TOPGEN], 1u);
;             else XB_SPIN(xb_ld(&bar[XB_TOPGEN]) == tg, bar);
;             __builtin_amdgcn_fence(__ATOMIC_ACQUIRE, "agent");
;             xb_add(&bar[XB_XGEN(b.x)], 1u);
;             asm volatile("s_waitcnt vmcnt(0)" ::: "memory");
;         } else {
;             XB_SPIN(xb_ld(&bar[XB_XGEN(b.x)]) == gen, bar);
;             __builtin_amdgcn_fence(__ATOMIC_ACQUIRE, "agent");
;             asm volatile("s_waitcnt vmcnt(0)" ::: "memory");
.LBB0_1168:
	s_or_b64 exec, exec, s[6:7]
	v_cvt_f32_u32_e32 v5, v3
	s_waitcnt vmcnt(0)
	v_readfirstlane_b32 s4, v4
	v_sub_u32_e32 v4, 0, v3
	v_rcp_iflag_f32_e32 v5, v5
	v_add_u32_e32 v6, s4, v2
	v_mul_f32_e32 v5, 0x4f7ffffe, v5
	v_cvt_u32_f32_e32 v5, v5
	v_mul_lo_u32 v2, v4, v5
	v_mul_hi_u32 v2, v5, v2
	v_add_u32_e32 v2, v5, v2
	v_mul_hi_u32 v2, v6, v2
	v_mul_lo_u32 v4, v2, v3
	v_sub_u32_e32 v4, v6, v4
	v_add_u32_e32 v5, 1, v2
	v_cmp_ge_u32_e32 vcc, v4, v3
	s_nop 1
	v_cndmask_b32_e32 v2, v2, v5, vcc
	v_sub_u32_e32 v5, v4, v3
	v_cndmask_b32_e32 v4, v4, v5, vcc
	v_add_u32_e32 v5, 1, v2
	v_cmp_ge_u32_e32 vcc, v4, v3
	v_add_u32_e32 v4, 1, v6
	s_nop 0
	v_cndmask_b32_e32 v2, v2, v5, vcc
	v_mul_lo_u32 v5, v3, v2
	v_add_u32_e32 v3, v5, v3
	v_cmp_ne_u32_e32 vcc, v4, v3
	s_and_saveexec_b64 s[4:5], vcc
	s_xor_b64 s[4:5], exec, s[4:5]
	s_cbranch_execz .LBB0_1182
	s_waitcnt lgkmcnt(0)
	v_add_u32_e32 v4, 1, v2
	v_mul_lo_u32 v4, v4, v1
	v_mov_b32_e32 v1, 0x3400
	global_load_dword v1, v1, s[30:31] sc1
	s_add_u32 s8, s30, 0x3400
	s_addc_u32 s9, s31, 0
	s_waitcnt vmcnt(0)
	v_cmp_lt_u32_e32 vcc, v1, v4
	s_and_saveexec_b64 s[6:7], vcc
	s_cbranch_execz .LBB0_1181
	s_mov_b32 s20, 1
	s_mov_b64 s[10:11], 0
	v_mov_b32_e32 v1, 0
	s_branch .LBB0_1172

; __device__ __forceinline__ unsigned xb_ld(unsigned* p)              { return __hip_atomic_load(p, __ATOMIC_RELAXED, __HIP_MEMORY_SCOPE_AGENT); }
; #define XB_SPIN(cond, bar) do { unsigned _sp = 0; while (cond) { __builtin_amdgcn_s_sleep(1); \
;     if ((++_sp & 255u) == 0u) { if (xb_ld(&(bar)[XB_TMO])) break; if (_sp > XB_SPIN_CAP) { atomicAdd(&(bar)[XB_TMO], 1u); break; } } } } while (0)
; __device__ __forceinline__ void xcd_barrier(const XcdBarrier& b) {
;     ...
;         } else {
;             XB_SPIN(xb_ld(&bar[XB_XGEN(b.x)]) == gen, bar);
;             __builtin_amdgcn_fence(__ATOMIC_ACQUIRE, "agent");
;             asm volatile("s_waitcnt vmcnt(0)" ::: "memory");
.LBB0_1174:
	global_load_dword v3, v1, s[8:9] sc1
	s_add_i32 s20, s20, 1
	s_mov_b64 s[16:17], -1
	s_waitcnt vmcnt(0)
	v_cmp_ge_u32_e32 vcc, v3, v4
	s_orn2_b64 s[14:15], vcc, exec
	s_branch .LBB0_1171

; __device__ __forceinline__ unsigned xb_ld(unsigned* p)              { return __hip_atomic_load(p, __ATOMIC_RELAXED, __HIP_MEMORY_SCOPE_AGENT); }
; __device__ __forceinline__ unsigned xb_add(unsigned* p, unsigned v) { return __hip_atomic_fetch_add(p, v, __ATOMIC_RELAXED, __HIP_MEMORY_SCOPE_AGENT); }
; #define XB_SPIN(cond, bar) do { unsigned _sp = 0; while (cond) { __builtin_amdgcn_s_sleep(1); \
;     if ((++_sp & 255u) == 0u) { if (xb_ld(&(bar)[XB_TMO])) break; if (_sp > XB_SPIN_CAP) { atomicAdd(&(bar)[XB_TMO], 1u); break; } } } } while (0)
; __device__ __forceinline__ void xcd_barrier(const XcdBarrier& b) {
;     ...
;             const unsigned og = xb_add(&bar[XB_TOP], 1u);
;             const unsigned tg = og / nx;
;             if (og + 1u == (tg + 1u) * nx) xb_add(&bar[XB_TOPGEN], 1u);
;             else XB_SPIN(xb_ld(&bar[XB_TOPGEN]) == tg, bar);
;             __builtin_amdgcn_fence(__ATOMIC_ACQUIRE, "agent");
.LBB0_1185:
	s_or_b64 exec, exec, s[8:9]
	v_cvt_f32_u32_e32 v4, v1
	s_waitcnt vmcnt(0)
	v_readfirstlane_b32 s6, v3
	s_add_u32 s8, s30, 0x3500
	s_addc_u32 s9, s31, 0
	v_rcp_iflag_f32_e32 v4, v4
	v_add_u32_e32 v2, s6, v2
	v_add_u32_e32 v5, 1, v2
	s_mov_b64 s[10:11], -1
	v_mul_f32_e32 v3, 0x4f7ffffe, v4
	v_cvt_u32_f32_e32 v3, v3
	v_sub_u32_e32 v4, 0, v1
	v_mul_lo_u32 v4, v4, v3
	v_mul_hi_u32 v4, v3, v4
	v_add_u32_e32 v3, v3, v4
	v_mul_hi_u32 v3, v2, v3
	v_mul_lo_u32 v4, v3, v1
	v_sub_u32_e32 v2, v2, v4
	v_add_u32_e32 v6, 1, v3
	v_cmp_ge_u32_e32 vcc, v2, v1
	v_sub_u32_e32 v4, v2, v1
	s_nop 0
	v_cndmask_b32_e32 v3, v3, v6, vcc
	v_cndmask_b32_e32 v2, v2, v4, vcc
	v_add_u32_e32 v4, 1, v3
	v_cmp_ge_u32_e32 vcc, v2, v1
	s_nop 1
	v_cndmask_b32_e32 v4, v3, v4, vcc
	v_mul_lo_u32 v2, v1, v4
	v_add_u32_e32 v1, v2, v1
	v_mov_b32_e32 v6, v1
	v_cmp_ne_u32_e32 vcc, v5, v1
	v_mov_b64_e32 v[2:3], s[8:9]
	s_and_saveexec_b64 s[6:7], vcc
	s_cbranch_execz .LBB0_1197
	v_mov_b32_e32 v1, 0
	global_load_dword v2, v1, s[8:9] offset:-256 sc1
	s_mov_b64 s[14:15], 0
	s_waitcnt vmcnt(0)
	v_cmp_lt_u32_e32 vcc, v2, v6
	s_and_saveexec_b64 s[12:13], vcc
	s_cbranch_execz .LBB0_1196
	s_add_u32 s10, s30, 0x200
	s_addc_u32 s11, s31, 0
	s_mov_b32 s24, 1
	s_branch .LBB0_1189

; __device__ __forceinline__ unsigned xb_ld(unsigned* p)              { return __hip_atomic_load(p, __ATOMIC_RELAXED, __HIP_MEMORY_SCOPE_AGENT); }
; __device__ __forceinline__ unsigned xb_add(unsigned* p, unsigned v) { return __hip_atomic_fetch_add(p, v, __ATOMIC_RELAXED, __HIP_MEMORY_SCOPE_AGENT); }
; #define XB_SPIN(cond, bar) do { unsigned _sp = 0; while (cond) { __builtin_amdgcn_s_sleep(1); \
;     if ((++_sp & 255u) == 0u) { if (xb_ld(&(bar)[XB_TMO])) break; if (_sp > XB_SPIN_CAP) { atomicAdd(&(bar)[XB_TMO], 1u); break; } } } } while (0)
; __device__ __forceinline__ void xcd_barrier(const XcdBarrier& b) {
;     ...
;             if (og + 1u == (tg + 1u) * nx) xb_add(&bar[XB_TOPGEN], 1u);
;             else XB_SPIN(xb_ld(&bar[XB_TOPGEN]) == tg, bar);
;             __builtin_amdgcn_fence(__ATOMIC_ACQUIRE, "agent");
.LBB0_1191:
	global_load_dword v2, v1, s[8:9] offset:-256 sc1
	s_add_i32 s24, s24, 1
	s_mov_b64 s[18:19], -1
	s_waitcnt vmcnt(0)
	v_cmp_ge_u32_e32 vcc, v2, v6
	s_orn2_b64 s[22:23], vcc, exec
	s_branch .LBB0_1188
